# attn: deep LDS prefetch in QK/PV, tile-major V^T + compact K buffers, QK prio 2, group-B prefetch issued after barrier
# speedup vs baseline: 1.5003x; 1.5003x over previous
; DI int opq(int x) { asm volatile("" : "+v"(x)); return x; }
; DI void diffprep_phase(const Params& p, const u16* proj, char* prep, char* smem) {
;   u16* VTP = reinterpret_cast<u16*>(prep);
;   u16* KS = VTP + SZ_VTP;
;   u16* VTS = KS + SZ_KS;
;   const int tid0 = opq(threadIdx.x), half = tid0 >> 8, tid = tid0 & 255;
;   u16* tl = reinterpret_cast<u16*>(smem) + half * (64 * 264);
;   for (int it = blockIdx.x * 2 + half; it < 2048; it += gridDim.x * 2) {
;     const int h = it & 7, c = (it >> 3) & 63, b = it >> 9;
;     const u16* src = proj + (size_t)(b * 4096 + c * 64) * 8192 + 4096 + h * 256;
;     __syncthreads();
; #pragma unroll
;     for (int i = 0; i < 8; ++i) {
;       const int id = tid + 256 * i, t = id >> 5, ch = id & 31;
;       *reinterpret_cast<u32x4*>(tl + t * 264 + ch * 8) = __builtin_nontemporal_load(reinterpret_cast<const u32x4*>(src + (size_t)t * 8192 + ch * 8));
.LBB0_947:
	s_or_b64 exec, exec, s[40:41]
	s_mov_b64 s[4:5], s[0:1]
	s_waitcnt lgkmcnt(0)
	s_barrier
	v_and_b32_e32 v1, 0xff, v208
	v_lshrrev_b32_e32 v2, 8, v208
	v_lshl_add_u32 v2, s2, 1, v2
	v_lshlrev_b32_e32 v3, 4, v1
	v_add_u32_e32 v3, 0x1000, v3
	v_lshrrev_b32_e32 v4, 5, v1
	v_and_b32_e32 v5, 31, v1
	v_lshlrev_b32_e32 v4, 21, v4
	v_lshl_add_u32 v4, v5, 4, v4
	s_lshl_b32 s4, s62, 1
	s_movk_i32 s5, 0x4000
.Lkp_loop:
	s_mov_b64 s[6:7], exec
	v_add_u32_e32 v12, s4, v2
	v_add_u32_e32 v13, s4, v12
	v_add_u32_e32 v14, s4, v13
	v_lshl_add_u32 v6, v2, 14, v3
	v_lshl_add_u32 v7, v12, 14, v3
	v_lshl_add_u32 v8, v13, 14, v3
	v_lshl_add_u32 v9, v14, 14, v3
	v_cmp_gt_u32_e32 vcc, s5, v2
	s_and_b64 exec, s[6:7], vcc
	global_load_dwordx4 v[16:19], v6, s[56:57] nt
	v_cmp_gt_u32_e32 vcc, s5, v12
	s_and_b64 exec, s[6:7], vcc
	global_load_dwordx4 v[20:23], v7, s[56:57] nt
	v_cmp_gt_u32_e32 vcc, s5, v13
	s_and_b64 exec, s[6:7], vcc
	global_load_dwordx4 v[24:27], v8, s[56:57] nt
	v_cmp_gt_u32_e32 vcc, s5, v14
	s_and_b64 exec, s[6:7], vcc
	global_load_dwordx4 v[28:31], v9, s[56:57] nt
	s_mov_b64 exec, s[6:7]
	v_lshrrev_b32_e32 v6, 12, v2
	v_and_b32_e32 v10, 0xfff, v2
	v_lshl_add_u32 v6, v6, 24, v4
	v_lshl_add_u32 v6, v10, 9, v6
	v_lshrrev_b32_e32 v7, 12, v12
	v_and_b32_e32 v10, 0xfff, v12
	v_lshl_add_u32 v7, v7, 24, v4
	v_lshl_add_u32 v7, v10, 9, v7
	v_lshrrev_b32_e32 v8, 12, v13
	v_and_b32_e32 v10, 0xfff, v13
	v_lshl_add_u32 v8, v8, 24, v4
	v_lshl_add_u32 v8, v10, 9, v8
	v_lshrrev_b32_e32 v9, 12, v14
	v_and_b32_e32 v10, 0xfff, v14
	v_lshl_add_u32 v9, v9, 24, v4
	v_lshl_add_u32 v9, v10, 9, v9
	v_cmp_gt_u32_e32 vcc, s5, v2
	s_and_b64 exec, s[6:7], vcc
	s_waitcnt vmcnt(3)
	global_store_dwordx4 v6, v[16:19], s[52:53]
	v_cmp_gt_u32_e32 vcc, s5, v12
	s_and_b64 exec, s[6:7], vcc
	s_waitcnt vmcnt(3)
	global_store_dwordx4 v7, v[20:23], s[52:53]
	v_cmp_gt_u32_e32 vcc, s5, v13
	s_and_b64 exec, s[6:7], vcc
	s_waitcnt vmcnt(3)
	global_store_dwordx4 v8, v[24:27], s[52:53]
	v_cmp_gt_u32_e32 vcc, s5, v14
	s_and_b64 exec, s[6:7], vcc
	s_waitcnt vmcnt(3)
	global_store_dwordx4 v9, v[28:31], s[52:53]
	s_mov_b64 exec, s[6:7]
	v_add_u32_e32 v2, s4, v14
	v_cmp_gt_u32_e32 vcc, s5, v2
	s_cbranch_vccnz .Lkp_loop
	v_mov_b32_e32 v39, v208
	v_readlane_b32 s4, v249, 18
	v_ashrrev_i32_e32 v20, 8, v39
	s_add_u32 s58, s46, 0x16d00000
	v_add_u32_e32 v41, s4, v20
	s_movk_i32 s4, 0x800
	s_addc_u32 s59, s47, 0
	v_and_b32_e32 v40, 0xff, v39
	v_cmp_gt_i32_e32 vcc, s4, v41
	v_lshlrev_b32_e32 v38, 3, v39
	v_lshl_add_u32 v42, v20, 8, s70
	s_and_saveexec_b64 s[8:9], vcc
	s_cbranch_execz .LBB0_950
	s_mov_b32 s4, 0x8400
	v_mad_i32_i24 v2, v20, s4, 0
	v_and_b32_e32 v0, 0xf8, v38
	v_lshl_add_u32 v7, v0, 1, v2
	v_lshl_add_u32 v21, v40, 1, v2
	v_lshrrev_b32_e32 v2, 5, v40
	v_lshlrev_b32_e32 v4, 13, v2
	v_mov_b32_e32 v1, 0
	v_mul_u32_u24_e32 v9, 0x210, v2
	v_or_b32_e32 v6, 0x10000, v4
	v_or_b32_e32 v8, 0x20000, v4
	v_or_b32_e32 v10, 0x30000, v4
	v_or_b32_e32 v12, 0x40000, v4
	v_or_b32_e32 v14, 0x50000, v4
	v_or_b32_e32 v16, 0x60000, v4
	v_or_b32_e32 v18, 0x70000, v4
	v_lshlrev_b32_e32 v2, 3, v20
	s_lshl_b32 s4, s62, 1
	v_lshl_add_u32 v22, v20, 8, s70
	s_lshl_b32 s5, s62, 9
	v_lshl_add_u32 v23, s2, 4, v2
	s_lshl_b32 s6, s62, 4
	s_mov_b64 s[10:11], 0
	v_lshlrev_b32_e32 v2, 1, v0
	v_mov_b32_e32 v3, v1
	s_mov_b64 s[12:13], 0x2000
	v_lshlrev_b32_e32 v4, 1, v4
	v_mov_b32_e32 v5, v1
	v_add_u32_e32 v24, v7, v9
	v_lshlrev_b32_e32 v6, 1, v6
	v_mov_b32_e32 v7, v1
	v_lshlrev_b32_e32 v8, 1, v8
	v_mov_b32_e32 v9, v1
	v_lshlrev_b32_e32 v10, 1, v10
	v_mov_b32_e32 v11, v1
	v_lshlrev_b32_e32 v12, 1, v12
	v_mov_b32_e32 v13, v1
	v_lshlrev_b32_e32 v14, 1, v14
	v_mov_b32_e32 v15, v1
	v_lshlrev_b32_e32 v16, 1, v16
	v_mov_b32_e32 v17, v1
	v_lshlrev_b32_e32 v18, 1, v18
	v_mov_b32_e32 v19, v1
	s_movk_i32 s7, 0x7ff
	v_mov_b32_e32 v25, v41
; DI void diffprep_phase(const Params& p, const u16* proj, char* prep, char* smem) {
;     ...
;   for (int it = blockIdx.x * 2 + half; it < 2048; it += gridDim.x * 2) {
;     const int h = it & 7, c = (it >> 3) & 63, b = it >> 9;
;     const u16* src = proj + (size_t)(b * 4096 + c * 64) * 8192 + 4096 + h * 256;
;     __syncthreads();
; #pragma unroll
;     for (int i = 0; i < 8; ++i) {
;       const int id = tid + 256 * i, t = id >> 5, ch = id & 31;
;       *reinterpret_cast<u32x4*>(tl + t * 264 + ch * 8) = __builtin_nontemporal_load(reinterpret_cast<const u32x4*>(src + (size_t)t * 8192 + ch * 8));
;     }
;     __syncthreads();
;     u16* dst = VTP + ((size_t)((b * 8 + h) * 256 + tid)) * 4096 + c * 64;
; #pragma unroll
;     for (int g16 = 0; g16 < 4; ++g16) {
;       u32 pk[8];
; #pragma unroll
;       for (int e = 0; e < 8; ++e) {
;         const int t = g16 * 16 + 2 * e;
;         pk[e] = (u32)tl[t * 264 + tid] | ((u32)tl[(t + 1) * 264 + tid] << 16);
;       }
;       u32x4 o0 = {pk[0], pk[1], pk[4], pk[5]}, o1 = {pk[2], pk[3], pk[6], pk[7]};
;       *reinterpret_cast<u32x4*>(dst + g16 * 16) = o0;
;       *reinterpret_cast<u32x4*>(dst + g16 * 16 + 8) = o1;
;     }
;   }
.LBB0_949:
	v_ashrrev_i32_e32 v27, 9, v25
	v_and_b32_e32 v30, 0xfc0, v23
	v_lshl_or_b32 v26, v27, 12, v30
	v_lshlrev_b32_e32 v29, 11, v27
	v_ashrrev_i32_e32 v27, 31, v26
	v_and_b32_e32 v28, 0x700, v22
	v_lshlrev_b64 v[26:27], 14, v[26:27]
	v_lshlrev_b32_e32 v0, 1, v28
	v_or_b32_e32 v28, v29, v28
	v_lshl_add_u64 v[26:27], s[56:57], 0, v[26:27]
	v_ashrrev_i32_e32 v29, 31, v28
	v_lshl_add_u64 v[26:27], v[26:27], 0, v[0:1]
	v_lshlrev_b64 v[28:29], 13, v[28:29]
	v_lshl_add_u64 v[26:27], v[26:27], 0, v[2:3]
	v_lshl_add_u64 v[28:29], s[58:59], 0, v[28:29]
	v_lshlrev_b32_e32 v0, 9, v30
	v_lshl_add_u32 v0, v40, 7, v0
	v_lshl_add_u64 v[26:27], v[26:27], 0, s[12:13]
	s_waitcnt vmcnt(0)
	v_lshl_add_u64 v[64:65], v[28:29], 0, v[0:1]
	v_lshl_add_u64 v[28:29], v[26:27], 0, v[4:5]
	v_lshl_add_u64 v[30:31], v[26:27], 0, v[6:7]
	v_lshl_add_u64 v[34:35], v[26:27], 0, v[8:9]
	v_lshl_add_u64 v[44:45], v[26:27], 0, v[10:11]
	v_lshl_add_u64 v[48:49], v[26:27], 0, v[12:13]
	v_lshl_add_u64 v[52:53], v[26:27], 0, v[14:15]
	v_lshl_add_u64 v[56:57], v[26:27], 0, v[16:17]
	v_lshl_add_u64 v[60:61], v[26:27], 0, v[18:19]
	s_barrier
	global_load_dwordx4 v[26:29], v[28:29], off nt
	s_nop 0
	global_load_dwordx4 v[30:33], v[30:31], off nt
	s_nop 0
	global_load_dwordx4 v[34:37], v[34:35], off nt
	s_nop 0
	global_load_dwordx4 v[44:47], v[44:45], off nt
	s_nop 0
	global_load_dwordx4 v[48:51], v[48:49], off nt
	s_nop 0
	global_load_dwordx4 v[52:55], v[52:53], off nt
	s_nop 0
	global_load_dwordx4 v[56:59], v[56:57], off nt
	s_nop 0
	global_load_dwordx4 v[60:63], v[60:61], off nt
	v_add_u32_e32 v25, s4, v25
	v_cmp_lt_i32_e32 vcc, s7, v25
	v_add_u32_e32 v22, s5, v22
	v_add_u32_e32 v23, s6, v23
	s_or_b64 s[10:11], vcc, s[10:11]
	s_waitcnt vmcnt(7)
	ds_write_b128 v24, v[26:29]
	s_waitcnt vmcnt(6)
	ds_write_b128 v24, v[30:33] offset:4224
	s_waitcnt vmcnt(5)
	ds_write_b128 v24, v[34:37] offset:8448
	s_waitcnt vmcnt(4)
	ds_write_b128 v24, v[44:47] offset:12672
	s_waitcnt vmcnt(3)
	ds_write_b128 v24, v[48:51] offset:16896
	s_waitcnt vmcnt(2)
	ds_write_b128 v24, v[52:55] offset:21120
	s_waitcnt vmcnt(1)
	ds_write_b128 v24, v[56:59] offset:25344
	s_waitcnt vmcnt(0)
	ds_write_b128 v24, v[60:63] offset:29568
	s_waitcnt lgkmcnt(0)
	s_barrier
	ds_read_u16 v0, v21 offset:3696
	ds_read_u16 v28, v21 offset:4224
	ds_read_u16 v29, v21 offset:4752
	ds_read_u16 v32, v21 offset:5280
	ds_read_u16 v33, v21 offset:5808
	ds_read_u16 v34, v21 offset:6336
	ds_read_u16 v35, v21 offset:6864
	ds_read_u16 v36, v21 offset:7392
	ds_read_u16 v37, v21 offset:7920
	ds_read_u16 v43, v21 offset:8448
	ds_read_u16 v44, v21 offset:8976
	ds_read_u16 v45, v21 offset:9504
	ds_read_u16 v46, v21 offset:10032
	ds_read_u16 v47, v21 offset:10560
	ds_read_u16 v48, v21 offset:11088
	ds_read_u16 v49, v21 offset:11616
	ds_read_u16 v50, v21 offset:12144
	ds_read_u16 v51, v21 offset:12672
	ds_read_u16 v52, v21 offset:13200
	ds_read_u16 v53, v21 offset:13728
	ds_read_u16 v54, v21 offset:14256
	ds_read_u16 v55, v21 offset:14784
	ds_read_u16 v56, v21 offset:15312
	ds_read_u16 v57, v21 offset:15840
	ds_read_u16 v58, v21 offset:16368
	ds_read_u16 v59, v21 offset:16896
	ds_read_u16 v60, v21 offset:17424
	ds_read_u16 v61, v21 offset:17952
	ds_read_u16 v62, v21 offset:18480
	ds_read_u16 v63, v21 offset:19008
	ds_read_u16 v66, v21 offset:19536
	ds_read_u16 v67, v21 offset:20064
	ds_read_u16 v68, v21 offset:20592
	ds_read_u16 v69, v21 offset:21120
	ds_read_u16 v70, v21 offset:21648
	ds_read_u16 v71, v21 offset:22176
	ds_read_u16 v72, v21 offset:22704
	ds_read_u16 v73, v21 offset:23232
	ds_read_u16 v74, v21 offset:23760
	ds_read_u16 v75, v21 offset:24288
	ds_read_u16 v76, v21 offset:24816
	ds_read_u16 v77, v21 offset:25344
	ds_read_u16 v78, v21 offset:25872
	ds_read_u16 v79, v21 offset:26400
	ds_read_u16 v80, v21 offset:26928
	ds_read_u16 v81, v21 offset:27456
	ds_read_u16 v82, v21 offset:27984
	ds_read_u16 v83, v21 offset:28512
	ds_read_u16 v84, v21 offset:29040
	ds_read_u16 v85, v21 offset:29568
	ds_read_u16 v86, v21 offset:30096
	ds_read_u16 v87, v21 offset:30624
	ds_read_u16 v88, v21 offset:31152
	ds_read_u16 v89, v21 offset:31680
	ds_read_u16 v90, v21 offset:32208
	ds_read_u16 v91, v21 offset:32736
	ds_read_u16 v26, v21
	ds_read_u16 v27, v21 offset:528
	ds_read_u16 v30, v21 offset:1056
	ds_read_u16 v31, v21 offset:1584
	ds_read_u16 v92, v21 offset:2112
	ds_read_u16 v93, v21 offset:2640
	ds_read_u16 v94, v21 offset:3168
	ds_read_u16 v95, v21 offset:33264
	s_waitcnt lgkmcnt(6)
	v_lshl_or_b32 v26, v27, 16, v26
	s_waitcnt lgkmcnt(4)
	v_lshl_or_b32 v27, v31, 16, v30
	v_lshl_or_b32 v28, v29, 16, v28
	v_lshl_or_b32 v29, v33, 16, v32
	s_waitcnt lgkmcnt(2)
	v_lshl_or_b32 v30, v93, 16, v92
	s_waitcnt lgkmcnt(1)
	v_lshl_or_b32 v31, v0, 16, v94
	v_lshl_or_b32 v32, v35, 16, v34
	v_lshl_or_b32 v33, v37, 16, v36
	v_lshl_or_b32 v34, v44, 16, v43
	v_lshl_or_b32 v35, v46, 16, v45
	v_lshl_or_b32 v44, v48, 16, v47
	v_lshl_or_b32 v45, v50, 16, v49
	v_lshl_or_b32 v36, v52, 16, v51
	v_lshl_or_b32 v37, v54, 16, v53
	v_lshl_or_b32 v46, v56, 16, v55
	v_lshl_or_b32 v47, v58, 16, v57
	v_lshl_or_b32 v48, v60, 16, v59
	v_lshl_or_b32 v49, v62, 16, v61
	v_lshl_or_b32 v52, v66, 16, v63
	v_lshl_or_b32 v53, v68, 16, v67
	v_lshl_or_b32 v50, v70, 16, v69
	v_lshl_or_b32 v51, v72, 16, v71
	v_lshl_or_b32 v54, v74, 16, v73
	v_lshl_or_b32 v55, v76, 16, v75
	v_lshl_or_b32 v56, v78, 16, v77
	v_lshl_or_b32 v57, v80, 16, v79
	v_lshl_or_b32 v60, v82, 16, v81
	v_lshl_or_b32 v61, v84, 16, v83
	v_lshl_or_b32 v58, v86, 16, v85
	v_lshl_or_b32 v59, v88, 16, v87
	v_lshl_or_b32 v62, v90, 16, v89
	s_waitcnt lgkmcnt(0)
	v_lshl_or_b32 v63, v95, 16, v91
	global_store_dwordx4 v[64:65], v[26:29], off
	global_store_dwordx4 v[64:65], v[30:33], off offset:16
	global_store_dwordx4 v[64:65], v[34:37], off offset:32
	global_store_dwordx4 v[64:65], v[44:47], off offset:48
	global_store_dwordx4 v[64:65], v[48:51], off offset:64
	global_store_dwordx4 v[64:65], v[52:55], off offset:80
	global_store_dwordx4 v[64:65], v[56:59], off offset:96
	global_store_dwordx4 v[64:65], v[60:63], off offset:112
	s_andn2_b64 exec, exec, s[10:11]
	s_cbranch_execnz .LBB0_949

; DI void attn_phase(const Params& p, const u16* proj, const char* prep, u16* obuf, char* smem) {
;     ...
;     int b, h, nt, nkeys, nq; size_t qrow0, kstride, khs, vtstride; const u16* kbase; const u16* vtbase;
;     if (i < 2048) {
;       const int c = 63 - (i >> 5), bh = i & 31; b = bh >> 3; h = bh & 7; nt = c + 1; nkeys = nt * 64; nq = 64;
;       qrow0 = (size_t)b * 4096 + c * 64;
;       kbase = proj + (size_t)(b * 4096) * 8192 + 2048 + (2 * h) * 128; kstride = 8192; khs = 128;
;       vtbase = VTP + (size_t)((b * 8 + h) * 256) * 4096; vtstride = 4096;
;     } else {
;       const int bh = i - 2048; b = bh >> 3; h = bh & 7; nt = 17; nkeys = 1056; nq = 32;
;       qrow0 = (size_t)PROWS + b * 32;
;       kbase = KS + (size_t)((b * 16 + 2 * h) * 1088) * 128; kstride = 128; khs = (size_t)1088 * 128;
;       vtbase = VTS + (size_t)((b * 8 + h) * 256) * 1088; vtstride = 1088;
;     }
;     bf16x8 Qf[8];
;     {
;       const size_t qrow = qrow0 + ((qt * 32 < nq) ? qt * 32 : 0) + l31;
;       const u16* qp = proj + qrow * 8192 + (2 * h + jh) * 128 + hh * 8;
; #pragma unroll
;       for (int s = 0; s < 8; ++s) Qf[s] = ld16(qp + s * 16);
; #pragma unroll
;       for (int s = 0; s < 8; ++s) asm volatile("" : "+v"(Qf[s]));
;     }
;     u32x4 kr[4], vr[4];
;     auto gload = [&](int kt) {
; #pragma unroll
;       for (int ii = 0; ii < 4; ++ii) {
;         const int id = tid + 512 * ii;
;         const int jl = id >> 10, key = (id >> 4) & 63, ch = id & 15;
;         kr[ii] = *reinterpret_cast<const u32x4*>(kbase + jl * khs + (size_t)(kt * 64 + key) * kstride + ch * 8);
;         const int vd = id >> 3, cv = id & 7;
;         vr[ii] = *reinterpret_cast<const u32x4*>(vtbase + (size_t)vd * vtstride + kt * 64 + cv * 8);
;       }
;     };
;     auto sstore = [&](int buf) {
;       u16* Ks = lds + buf * BUFE; u16* Vt = Ks + 2 * 64 * 136;
; #pragma unroll
;       for (int ii = 0; ii < 4; ++ii) {
;         const int id = tid + 512 * ii;
;         const int jl = id >> 10, key = (id >> 4) & 63, ch = id & 15;
;         *reinterpret_cast<u32x4*>(Ks + (jl * 64 + key) * 136 + ch * 8) = kr[ii];
;         const int vd = id >> 3, cv = id & 7;
;         *reinterpret_cast<u32x4*>(Vt + vd * 72 + cv * 8) = vr[ii];
;       }
;     };
;     float m = -1e30f, l = 0.f;
;     f32x16 O[4];
; #pragma unroll
;     for (int vt = 0; vt < 4; ++vt) O[vt] = zero16();
;     ...
;     const bool grpB = vh != 0;
.LBB0_1025:
	s_andn2_b64 vcc, exec, s[14:15]
	s_cbranch_vccnz .LBB0_1027
	s_ashr_i32 s10, s16, 5
	s_bfe_u32 s11, s16, 0x20003
	s_sub_i32 s65, 64, s10
	s_lshl_b32 s12, s11, 12
	s_lshl_b32 s10, s10, 6
	s_sub_i32 s10, s12, s10
	s_lshl_b32 s66, s65, 6
	s_add_i32 s78, s10, 0xfc0
	s_lshl_b32 s10, s16, 21
	s_and_b32 s10, s10, 0x3e00000
	s_add_u32 s10, s52, s10
	s_addc_u32 s11, s53, 0
	s_lshl_b32 s12, s16, 8
	s_and_b32 s84, s12, 0x700
	s_lshl_b32 s12, s16, 21
	s_and_b32 s12, s12, 0x3e00000
	s_add_u32 s12, s58, s12
	s_mov_b32 s64, 64
	s_mov_b64 s[14:15], 0x40
	s_movk_i32 s32, 0x200
	s_addc_u32 s13, s59, 0
	s_mov_b64 s[86:87], 0x100
	s_mov_b64 s[16:17], 0x80
	s_mov_b64 s[48:49], s[78:79]
	s_branch .LBB0_1028
.LBB0_1027:
	s_mov_b32 s65, 17
	s_movk_i32 s66, 0x420
	s_mov_b32 s64, 32
	s_mov_b64 s[14:15], 0x440
	s_mov_b32 s32, 2
	s_mov_b64 s[86:87], 0x80
	s_mov_b64 s[16:17], 0x22000
.LBB0_1028:
	s_cmp_lt_u32 s96, s64
	s_cselect_b32 s15, s96, 0
	s_add_u32 s18, s15, s48
	s_addc_u32 s19, 0, s49
	v_lshl_add_u64 v[0:1], s[18:19], 0, v[160:161]
	v_lshlrev_b64 v[0:1], 14, v[0:1]
	v_lshl_add_u64 v[0:1], s[56:57], 0, v[0:1]
	s_or_b32 s78, s84, s97
	v_lshl_add_u64 v[0:1], s[78:79], 1, v[0:1]
	v_lshlrev_b32_e32 v180, 1, v164
	v_mov_b32_e32 v181, v163
	v_lshl_add_u64 v[0:1], v[0:1], 0, v[180:181]
	global_load_dwordx4 v[96:99], v[0:1], off
	global_load_dwordx4 v[100:103], v[0:1], off offset:32
	global_load_dwordx4 v[104:107], v[0:1], off offset:64
	global_load_dwordx4 v[108:111], v[0:1], off offset:96
	global_load_dwordx4 v[112:115], v[0:1], off offset:128
	global_load_dwordx4 v[116:119], v[0:1], off offset:160
	global_load_dwordx4 v[120:123], v[0:1], off offset:192
	global_load_dwordx4 v[124:127], v[0:1], off offset:224
	v_mul_hi_i32_i24_e32 v1, s16, v167
	v_mul_i32_i24_e32 v0, s16, v167
	v_mul_u32_u24_e32 v8, s86, v169
	s_waitcnt vmcnt(0)
	v_mov_b32_e32 v9, v163
	v_mad_i64_i32 v[2:3], s[18:19], s14, v168, 0
	v_mul_hi_i32_i24_e32 v5, s16, v171
	v_mul_i32_i24_e32 v4, s16, v171
	v_mul_u32_u24_e32 v10, s86, v173
	v_mad_i64_i32 v[6:7], s[18:19], s14, v172, 0
	v_mul_hi_i32_i24_e32 v13, s16, v175
	v_mul_i32_i24_e32 v12, s16, v175
	v_mad_i64_i32 v[14:15], s[18:19], s14, v174, 0
	v_mul_hi_i32_i24_e32 v17, s16, v177
	v_mul_i32_i24_e32 v16, s16, v177
	v_mul_u32_u24_e32 v18, s86, v200
	v_mad_i64_i32 v[20:21], s[14:15], s14, v176, 0
	v_lshl_add_u64 v[0:1], v[0:1], 1, s[10:11]
	v_lshlrev_b32_e32 v8, 1, v8
	v_lshlrev_b32_e32 v162, 1, v166
	v_lshlrev_b32_e32 v182, 1, v170
	v_mov_b32_e32 v183, v163
	v_mov_b32_e32 v11, v163
	v_mov_b32_e32 v19, v163
	v_lshl_add_u64 v[22:23], v[2:3], 1, s[12:13]
	v_lshl_add_u64 v[2:3], v[4:5], 1, s[10:11]
	v_lshlrev_b32_e32 v10, 1, v10
	v_lshl_add_u64 v[24:25], v[6:7], 1, s[12:13]
	v_lshl_add_u64 v[4:5], v[12:13], 1, s[10:11]
	v_lshl_add_u64 v[12:13], v[14:15], 1, s[12:13]
	v_lshl_add_u64 v[6:7], v[16:17], 1, s[10:11]
	v_lshlrev_b32_e32 v18, 1, v18
	v_lshl_add_u64 v[14:15], v[20:21], 1, s[12:13]
	v_lshl_add_u64 v[16:17], v[0:1], 0, v[8:9]
	v_lshl_add_u64 v[10:11], v[2:3], 0, v[10:11]
	v_lshl_add_u64 v[8:9], v[4:5], 0, v[8:9]
	v_lshl_add_u64 v[188:189], v[12:13], 0, v[182:183]
	v_lshl_add_u64 v[12:13], v[6:7], 0, v[18:19]
	v_lshl_add_u64 v[190:191], v[14:15], 0, v[182:183]
	v_lshl_add_u64 v[14:15], v[16:17], 0, v[162:163]
	v_lshl_add_u64 v[184:185], v[22:23], 0, v[182:183]
	v_lshl_add_u64 v[186:187], v[24:25], 0, v[182:183]
	v_lshl_add_u64 v[10:11], v[10:11], 0, v[162:163]
	v_lshl_add_u64 v[8:9], v[8:9], 0, v[162:163]
	v_lshl_add_u64 v[12:13], v[12:13], 0, v[162:163]
	s_cmp_lt_u32 s65, 2
	s_waitcnt vmcnt(0)
	global_load_dwordx4 v[128:131], v[14:15], off
	global_load_dwordx4 v[132:135], v[184:185], off
	global_load_dwordx4 v[136:139], v[10:11], off
	global_load_dwordx4 v[140:143], v[186:187], off
	global_load_dwordx4 v[144:147], v[8:9], off
	global_load_dwordx4 v[148:151], v[188:189], off
	global_load_dwordx4 v[152:155], v[12:13], off
	global_load_dwordx4 v[156:159], v[190:191], off
	s_barrier
	s_waitcnt vmcnt(7)
	ds_write_b128 v202, v[128:131]
	s_waitcnt vmcnt(6)
	ds_write_b128 v204, v[132:135] offset:34816
	s_waitcnt vmcnt(5)
	ds_write_b128 v206, v[136:139]
	s_waitcnt vmcnt(4)
	ds_write_b128 v210, v[140:143] offset:34816
	s_waitcnt vmcnt(3)
	ds_write_b128 v212, v[144:147]
	s_waitcnt vmcnt(2)
	ds_write_b128 v214, v[148:151] offset:34816
	s_waitcnt vmcnt(1)
	ds_write_b128 v216, v[152:155]
	s_waitcnt vmcnt(0)
	ds_write_b128 v218, v[156:159] offset:34816
	s_waitcnt lgkmcnt(0)
	s_barrier
	s_cbranch_scc1 .LBB0_1030
	s_lshl_b32 s14, s32, 6
	s_mov_b32 s15, 0
	v_mul_u32_u24_e32 v8, s86, v219
	v_lshlrev_b32_e32 v8, 1, v8
	v_mov_b32_e32 v9, v163
	v_mul_u32_u24_e32 v12, s86, v220
	v_lshl_add_u64 v[10:11], v[0:1], 0, v[8:9]
	v_lshlrev_b32_e32 v12, 1, v12
	v_mov_b32_e32 v13, v163
	v_lshl_add_u64 v[10:11], v[10:11], 0, v[162:163]
	v_lshl_add_u64 v[12:13], v[2:3], 0, v[12:13]
	v_lshl_add_u64 v[12:13], v[12:13], 0, v[162:163]
	global_load_dwordx4 v[128:131], v[10:11], off
	global_load_dwordx4 v[136:139], v[12:13], off
	v_lshl_add_u64 v[14:15], v[184:185], 0, s[14:15]
	v_lshl_add_u64 v[16:17], v[186:187], 0, s[14:15]
	global_load_dwordx4 v[132:135], v[14:15], off
	global_load_dwordx4 v[140:143], v[16:17], off
	v_mul_u32_u24_e32 v10, s86, v221
	v_lshl_add_u64 v[8:9], v[4:5], 0, v[8:9]
	v_lshlrev_b32_e32 v10, 1, v10
	v_mov_b32_e32 v11, v163
	v_lshl_add_u64 v[8:9], v[8:9], 0, v[162:163]
	v_lshl_add_u64 v[10:11], v[6:7], 0, v[10:11]
	v_lshl_add_u64 v[10:11], v[10:11], 0, v[162:163]
	global_load_dwordx4 v[144:147], v[8:9], off
	global_load_dwordx4 v[152:155], v[10:11], off
	v_lshl_add_u64 v[14:15], v[188:189], 0, s[14:15]
	v_lshl_add_u64 v[16:17], v[190:191], 0, s[14:15]
	global_load_dwordx4 v[148:151], v[14:15], off
	global_load_dwordx4 v[156:159], v[16:17], off

; #define MFMA(a, b, c) __builtin_amdgcn_mfma_f32_32x32x16_bf16((a), (b), (c), 0, 0, 0)
; DI int crow(int reg, int hh) { return (reg & 3) + 8 * (reg >> 2) + 4 * hh; }
; DI void attn_phase(const Params& p, const u16* proj, const char* prep, u16* obuf, char* smem) {
;     ...
;       const u16* Ks = lds + (kt & 1) * BUFE; const u16* Vt = Ks + 2 * 64 * 136;
;       f32x16 st[2];
;       __builtin_amdgcn_s_setprio(1);
; #pragma unroll
;       for (int kti = 0; kti < 2; ++kti) {
;         st[kti] = zero16();
; #pragma unroll
;         for (int s = 0; s < 8; ++s) {
;           const bf16x8 a = ld16(Ks + (jh * 64 + kti * 32 + l31) * 136 + s * 16 + hh * 8);
;           st[kti] = MFMA(a, Qf[s], st[kti]);
;         }
;       }
;       __builtin_amdgcn_s_setprio(0);
;       constexpr float SC = 0.08838834764831845f * 1.4426950408889634f;
;       if ((kt + 1) * 64 > nkeys) {
; #pragma unroll
;         for (int kti = 0; kti < 2; ++kti)
; #pragma unroll
;           for (int reg = 0; reg < 16; ++reg)
;             if (kt * 64 + kti * 32 + crow(reg, hh) >= nkeys) st[kti][reg] = -1e30f;
;       }
.LBB0_1033:
	s_bitcmp1_b32 s67, 0
	s_cselect_b32 s10, 0x11800, 0
	s_add_i32 s85, s10, 0
	s_setprio 2
	v_lshl_add_u32 v233, v164, 1, s85
	v_add_u32_e32 v232, v233, v224
	ds_read_b128 v[64:67], v232
	ds_read_b128 v[68:71], v232 offset:32
	ds_read_b128 v[72:75], v232 offset:64
	ds_read_b128 v[76:79], v232 offset:96
	ds_read_b128 v[236:239], v232 offset:128
	ds_read_b128 v[240:243], v232 offset:160
	ds_read_b128 v[244:247], v232 offset:192
	s_waitcnt lgkmcnt(6)
	v_mfma_f32_32x32x16_bf16 v[80:95], v[64:67], v[96:99], 0
	s_waitcnt lgkmcnt(5)
	v_mfma_f32_32x32x16_bf16 v[80:95], v[68:71], v[100:103], v[80:95]
	ds_read_b128 v[64:67], v232 offset:224
	s_waitcnt lgkmcnt(5)
	v_mfma_f32_32x32x16_bf16 v[80:95], v[72:75], v[104:107], v[80:95]
	s_waitcnt lgkmcnt(4)
	v_mfma_f32_32x32x16_bf16 v[80:95], v[76:79], v[108:111], v[80:95]
	ds_read_b128 v[68:71], v232 offset:8704
	s_waitcnt lgkmcnt(4)
	v_mfma_f32_32x32x16_bf16 v[80:95], v[236:239], v[112:115], v[80:95]
	ds_read_b128 v[236:239], v232 offset:8736
	s_waitcnt lgkmcnt(4)
	v_mfma_f32_32x32x16_bf16 v[80:95], v[240:243], v[116:119], v[80:95]
	ds_read_b128 v[240:243], v232 offset:8768
	s_waitcnt lgkmcnt(4)
	v_mfma_f32_32x32x16_bf16 v[80:95], v[244:247], v[120:123], v[80:95]
	ds_read_b128 v[244:247], v232 offset:8800
	s_waitcnt lgkmcnt(4)
	v_mfma_f32_32x32x16_bf16 v[80:95], v[64:67], v[124:127], v[80:95]
	s_waitcnt lgkmcnt(3)
	v_mfma_f32_32x32x16_bf16 v[64:79], v[68:71], v[96:99], 0
	s_waitcnt lgkmcnt(2)
	v_mfma_f32_32x32x16_bf16 v[64:79], v[236:239], v[100:103], v[64:79]
	ds_read_b128 v[236:239], v232 offset:8832
	s_waitcnt lgkmcnt(2)
	v_mfma_f32_32x32x16_bf16 v[64:79], v[240:243], v[104:107], v[64:79]
	ds_read_b128 v[240:243], v232 offset:8864
	s_waitcnt lgkmcnt(2)
	v_mfma_f32_32x32x16_bf16 v[64:79], v[244:247], v[108:111], v[64:79]
	ds_read_b128 v[244:247], v232 offset:8896
	s_waitcnt lgkmcnt(2)
	v_mfma_f32_32x32x16_bf16 v[64:79], v[236:239], v[112:115], v[64:79]
	ds_read_b128 v[236:239], v232 offset:8928
	s_waitcnt lgkmcnt(2)
	v_mfma_f32_32x32x16_bf16 v[64:79], v[240:243], v[116:119], v[64:79]
	s_waitcnt lgkmcnt(1)
	v_mfma_f32_32x32x16_bf16 v[64:79], v[244:247], v[120:123], v[64:79]
	s_waitcnt lgkmcnt(0)
	v_mfma_f32_32x32x16_bf16 v[64:79], v[236:239], v[124:127], v[64:79]
	s_setprio 0
	s_sub_i32 s10, s78, 64
	s_cmp_le_i32 s10, s66
	s_cbranch_scc1 .LBB0_1035
	v_add_u32_e32 v232, s78, v222
	v_add_u32_e32 v235, 0xffffff80, v232
	v_cmp_gt_i32_e32 vcc, s66, v235
	v_add_u32_e32 v235, 0xffffff81, v232
	v_cmp_gt_i32_e64 s[10:11], s66, v235
	s_or_b64 vcc, s[10:11], vcc
	v_add_u32_e32 v235, 0xffffff82, v232
	v_cndmask_b32_e32 v80, v229, v80, vcc
	v_cmp_gt_i32_e32 vcc, s66, v235
	v_add_u32_e32 v235, 0xffffff83, v232
	v_cndmask_b32_e64 v81, v229, v81, s[10:11]
	v_cndmask_b32_e32 v82, v229, v82, vcc
	v_cmp_gt_i32_e32 vcc, s66, v235
	v_add_u32_e32 v235, 0xffffff88, v232
	s_nop 0
	v_cndmask_b32_e32 v83, v229, v83, vcc
	v_cmp_gt_i32_e32 vcc, s66, v235
	v_add_u32_e32 v235, 0xffffff89, v232
	s_nop 0
	v_cndmask_b32_e32 v84, v229, v84, vcc
	v_cmp_gt_i32_e32 vcc, s66, v235
	v_add_u32_e32 v235, 0xffffff8a, v232
	s_nop 0
	v_cndmask_b32_e32 v85, v229, v85, vcc
	v_cmp_gt_i32_e32 vcc, s66, v235
	v_add_u32_e32 v235, 0xffffff8b, v232
	s_nop 0
	v_cndmask_b32_e32 v86, v229, v86, vcc
	v_cmp_gt_i32_e32 vcc, s66, v235
	v_add_u32_e32 v235, 0xffffff90, v232
	s_nop 0
	v_cndmask_b32_e32 v87, v229, v87, vcc
	v_cmp_gt_i32_e32 vcc, s66, v235
	v_add_u32_e32 v235, 0xffffff91, v232
	s_nop 0
	v_cndmask_b32_e32 v88, v229, v88, vcc
	v_cmp_gt_i32_e32 vcc, s66, v235
	v_add_u32_e32 v235, 0xffffff92, v232
	s_nop 0
	v_cndmask_b32_e32 v89, v229, v89, vcc
	v_cmp_gt_i32_e32 vcc, s66, v235
	v_add_u32_e32 v235, 0xffffff93, v232
	s_nop 0
	v_cndmask_b32_e32 v90, v229, v90, vcc
	v_cmp_gt_i32_e32 vcc, s66, v235
	v_add_u32_e32 v235, 0xffffff98, v232
	s_nop 0
	v_cndmask_b32_e32 v91, v229, v91, vcc
	v_cmp_gt_i32_e32 vcc, s66, v235
	v_add_u32_e32 v235, 0xffffff99, v232
	s_nop 0
	v_cndmask_b32_e32 v92, v229, v92, vcc
	v_cmp_gt_i32_e32 vcc, s66, v235
	v_add_u32_e32 v235, 0xffffff9a, v232
	s_nop 0
	v_cndmask_b32_e32 v93, v229, v93, vcc
	v_cmp_gt_i32_e32 vcc, s66, v235
	v_add_u32_e32 v235, 0xffffff9b, v232
	s_nop 0
	v_cndmask_b32_e32 v94, v229, v94, vcc
	v_cmp_gt_i32_e32 vcc, s66, v235
	v_add_u32_e32 v235, 0xffffffa0, v232
	v_cmp_gt_i32_e64 s[10:11], s66, v235
	v_add_u32_e32 v235, 0xffffffa1, v232
	v_cmp_gt_i32_e64 s[12:13], s66, v235
	v_add_u32_e32 v235, 0xffffffa2, v232
	v_cmp_gt_i32_e64 s[14:15], s66, v235
	v_add_u32_e32 v235, 0xffffffa3, v232
	v_cmp_gt_i32_e64 s[16:17], s66, v235
	v_add_u32_e32 v235, 0xffffffa8, v232
	v_cmp_gt_i32_e64 s[18:19], s66, v235
	v_add_u32_e32 v235, 0xffffffa9, v232
	v_cmp_gt_i32_e64 s[20:21], s66, v235
	v_add_u32_e32 v235, 0xffffffaa, v232
	v_cmp_gt_i32_e64 s[22:23], s66, v235
	v_add_u32_e32 v235, 0xffffffab, v232
	v_cmp_gt_i32_e64 s[24:25], s66, v235
	v_add_u32_e32 v235, 0xffffffb0, v232
	v_cmp_gt_i32_e64 s[26:27], s66, v235
	v_add_u32_e32 v235, 0xffffffb1, v232
	v_cmp_gt_i32_e64 s[28:29], s66, v235
	v_add_u32_e32 v235, 0xffffffb2, v232
	v_cmp_gt_i32_e64 s[30:31], s66, v235
	v_add_u32_e32 v235, 0xffffffb3, v232
	v_cmp_gt_i32_e64 s[34:35], s66, v235
	v_add_u32_e32 v235, 0xffffffb8, v232
	v_cmp_gt_i32_e64 s[36:37], s66, v235
	v_add_u32_e32 v235, 0xffffffb9, v232
	v_cmp_gt_i32_e64 s[38:39], s66, v235
	v_add_u32_e32 v235, 0xffffffba, v232
	v_add_u32_e32 v232, 0xffffffbb, v232
	v_cmp_gt_i32_e64 s[40:41], s66, v235
	v_cmp_gt_i32_e64 s[42:43], s66, v232
	s_or_b64 s[40:41], s[42:43], s[40:41]
	s_or_b64 s[38:39], s[40:41], s[38:39]
	s_or_b64 s[36:37], s[38:39], s[36:37]
	s_or_b64 s[34:35], s[36:37], s[34:35]
	s_or_b64 s[30:31], s[34:35], s[30:31]
	s_or_b64 s[28:29], s[30:31], s[28:29]
	s_or_b64 s[26:27], s[28:29], s[26:27]
	s_or_b64 s[24:25], s[26:27], s[24:25]
	s_or_b64 s[22:23], s[24:25], s[22:23]
	s_or_b64 s[20:21], s[22:23], s[20:21]
	s_or_b64 s[18:19], s[20:21], s[18:19]
	s_or_b64 s[16:17], s[18:19], s[16:17]
	s_or_b64 s[14:15], s[16:17], s[14:15]
	s_or_b64 s[12:13], s[14:15], s[12:13]
	s_or_b64 s[10:11], s[12:13], s[10:11]
	s_or_b64 vcc, s[10:11], vcc
	v_cndmask_b32_e64 v79, v229, v79, s[42:43]
	v_cndmask_b32_e64 v78, v229, v78, s[40:41]
	v_cndmask_b32_e64 v77, v229, v77, s[38:39]
	v_cndmask_b32_e64 v76, v229, v76, s[36:37]
	v_cndmask_b32_e64 v75, v229, v75, s[34:35]
	v_cndmask_b32_e64 v74, v229, v74, s[30:31]
	v_cndmask_b32_e64 v73, v229, v73, s[28:29]
	v_cndmask_b32_e64 v72, v229, v72, s[26:27]
	v_cndmask_b32_e64 v71, v229, v71, s[24:25]
	v_cndmask_b32_e64 v70, v229, v70, s[22:23]
	v_cndmask_b32_e64 v69, v229, v69, s[20:21]
	v_cndmask_b32_e64 v68, v229, v68, s[18:19]
	v_cndmask_b32_e64 v67, v229, v67, s[16:17]
	v_cndmask_b32_e64 v66, v229, v66, s[14:15]
	v_cndmask_b32_e64 v65, v229, v65, s[12:13]
	v_cndmask_b32_e64 v64, v229, v64, s[10:11]
	v_cndmask_b32_e32 v95, v229, v95, vcc

; #define MFMA(a, b, c) __builtin_amdgcn_mfma_f32_32x32x16_bf16((a), (b), (c), 0, 0, 0)
; #define ATT_BAR() do { asm volatile("s_waitcnt lgkmcnt(0)" ::: "memory"); __builtin_amdgcn_s_barrier(); asm volatile("" ::: "memory"); } while (0)
; DI void attn_phase(const Params& p, const u16* proj, const char* prep, u16* obuf, char* smem) {
;     ...
;       if (grpB && kt + 1 < nt) { sstore((kt + 1) & 1); if (kt + 2 < nt) gload(kt + 2); }
;       ATT_BAR();
;       __builtin_amdgcn_s_setprio(1);
; #pragma unroll
;       for (int kti = 0; kti < 2; ++kti) {
;         {
;           const bf16x8 pf = packacc<0>(st[kti]);
; #pragma unroll
;           for (int vt = 0; vt < 4; ++vt) {
;             O[vt] = MFMA(ld16(Vt + ((vh * 4 + vt) * 32 + l31) * 72 + kti * 32 + 8 * hh), pf, O[vt]);
;           }
;         }
;         {
;           const bf16x8 pf = packacc<1>(st[kti]);
; #pragma unroll
;           for (int vt = 0; vt < 4; ++vt) {
;             O[vt] = MFMA(ld16(Vt + ((vh * 4 + vt) * 32 + l31) * 72 + kti * 32 + 16 + 8 * hh), pf, O[vt]);
;           }
;         }
;       }
;       __builtin_amdgcn_s_setprio(0);
;       if (!grpB && kt + 1 < nt) { sstore((kt + 1) & 1); if (kt + 2 < nt) gload(kt + 2); }
.LBB0_1037:
	s_add_i32 s12, s67, 1
	s_cmp_lt_i32 s12, s65
	s_cselect_b64 s[10:11], -1, 0
	s_and_b64 s[14:15], s[76:77], s[10:11]
	s_andn2_b64 vcc, exec, s[14:15]
	s_cbranch_vccnz .LBB0_1040
	s_bitcmp1_b32 s12, 0
	s_cselect_b32 s13, 0x11800, 0
	s_add_i32 s13, s13, 0
	v_add3_u32 v74, s13, v201, v162
	s_waitcnt vmcnt(7)
	ds_write_b128 v74, v[128:131]
	v_add3_u32 v74, s13, v203, v182
	s_waitcnt vmcnt(5)
	ds_write_b128 v74, v[132:135] offset:34816
	v_add3_u32 v74, s13, v205, v162
	s_waitcnt vmcnt(3)
	ds_write_b128 v74, v[136:139]
	v_add3_u32 v74, s13, v207, v182
	s_waitcnt vmcnt(1)
	ds_write_b128 v74, v[140:143] offset:34816
	v_add3_u32 v74, s13, v211, v162
	s_waitcnt vmcnt(3)
	ds_write_b128 v74, v[144:147]
	v_add3_u32 v74, s13, v213, v182
	s_waitcnt vmcnt(1)
	ds_write_b128 v74, v[148:151] offset:34816
	v_add3_u32 v74, s13, v215, v162
	ds_write_b128 v74, v[152:155]
	v_add3_u32 v74, s13, v217, v182
	s_waitcnt vmcnt(0)
	ds_write_b128 v74, v[156:159] offset:34816
.LBB0_1040:
	s_waitcnt lgkmcnt(0)
	s_barrier
	s_andn2_b64 vcc, exec, s[76:77]
	s_cbranch_vccnz .Lskip_gl_b
	s_add_i32 s13, s67, 2
	s_cmp_ge_i32 s13, s65
	s_cbranch_scc1 .Lskip_gl_b
	v_add_u32_e32 v74, s78, v169
	v_mad_u64_u32 v[74:75], s[14:15], s86, v74, 0
	v_lshlrev_b64 v[74:75], 1, v[74:75]
	v_lshl_add_u64 v[76:77], v[192:193], 0, v[74:75]
	s_mul_i32 s14, s78, s32
	s_mov_b32 s15, 0
	v_lshl_add_u64 v[74:75], v[196:197], 0, v[74:75]
	global_load_dwordx4 v[128:131], v[76:77], off
	global_load_dwordx4 v[144:147], v[74:75], off
	v_lshl_add_u64 v[76:77], v[184:185], 0, s[14:15]
	v_lshl_add_u64 v[74:75], v[188:189], 0, s[14:15]
	global_load_dwordx4 v[132:135], v[76:77], off
	global_load_dwordx4 v[148:151], v[74:75], off
	v_add_u32_e32 v76, s78, v173
	v_add_u32_e32 v74, s78, v200
	v_mad_u64_u32 v[76:77], s[16:17], s86, v76, 0
	v_mad_u64_u32 v[74:75], s[16:17], s86, v74, 0
	v_lshl_add_u64 v[76:77], v[76:77], 1, v[194:195]
	v_lshl_add_u64 v[74:75], v[74:75], 1, v[198:199]
	global_load_dwordx4 v[136:139], v[76:77], off
	global_load_dwordx4 v[152:155], v[74:75], off
	v_lshl_add_u64 v[76:77], v[186:187], 0, s[14:15]
	v_lshl_add_u64 v[74:75], v[190:191], 0, s[14:15]
	global_load_dwordx4 v[140:143], v[76:77], off
	global_load_dwordx4 v[156:159], v[74:75], off
.Lskip_gl_b:
	s_setprio 1
	v_add_u32_e32 v233, v233, v226
	ds_read_b128 v[244:247], v233 offset:34816
	v_cvt_pk_bf16_f32 v74, v235, v236
	v_cvt_pk_bf16_f32 v75, v237, v238
	v_cvt_pk_bf16_f32 v76, v239, v240
	v_cvt_pk_bf16_f32 v77, v241, v242
	ds_read_b128 v[236:239], v233 offset:39424
	ds_read_b128 v[240:243], v233 offset:44032
	v_cvt_pk_bf16_f32 v80, v80, v81
	v_cvt_pk_bf16_f32 v81, v82, v83
	v_cvt_pk_bf16_f32 v82, v84, v85
	v_cvt_pk_bf16_f32 v83, v87, v89
	v_cvt_pk_bf16_f32 v84, v86, v88
	v_cvt_pk_bf16_f32 v85, v90, v91
	v_cvt_pk_bf16_f32 v86, v92, v93
	v_cvt_pk_bf16_f32 v87, v94, v95
	ds_read_b128 v[88:91], v233 offset:48640
	ds_read_b128 v[92:95], v233 offset:34848
	v_cvt_pk_bf16_f32 v66, v66, v67
	v_cvt_pk_bf16_f32 v67, v68, v69
	v_cvt_pk_bf16_f32 v68, v70, v71
	v_cvt_pk_bf16_f32 v69, v72, v73
	ds_read_b128 v[70:73], v233 offset:39456
	s_waitcnt lgkmcnt(5)
	v_mfma_f32_32x32x16_bf16 v[48:63], v[244:247], v[74:77], v[48:63]
	ds_read_b128 v[244:247], v233 offset:44064
	s_waitcnt lgkmcnt(5)
	v_mfma_f32_32x32x16_bf16 v[32:47], v[236:239], v[74:77], v[32:47]
	ds_read_b128 v[236:239], v233 offset:48672
	s_waitcnt lgkmcnt(5)
	v_mfma_f32_32x32x16_bf16 v[16:31], v[240:243], v[74:77], v[16:31]
	ds_read_b128 v[240:243], v233 offset:34880
	s_waitcnt lgkmcnt(5)
	v_mfma_f32_32x32x16_bf16 v[0:15], v[88:91], v[74:77], v[0:15]
	ds_read_b128 v[88:91], v233 offset:39488
	s_waitcnt lgkmcnt(5)
	v_mfma_f32_32x32x16_bf16 v[48:63], v[92:95], v[80:83], v[48:63]
	ds_read_b128 v[92:95], v233 offset:44096
	s_waitcnt lgkmcnt(5)
	v_mfma_f32_32x32x16_bf16 v[32:47], v[70:73], v[80:83], v[32:47]
	ds_read_b128 v[70:73], v233 offset:48704
	s_waitcnt lgkmcnt(5)
	v_mfma_f32_32x32x16_bf16 v[16:31], v[244:247], v[80:83], v[16:31]
	ds_read_b128 v[244:247], v233 offset:34912
	s_waitcnt lgkmcnt(5)
	v_mfma_f32_32x32x16_bf16 v[0:15], v[236:239], v[80:83], v[0:15]
	ds_read_b128 v[236:239], v233 offset:39520
	s_waitcnt lgkmcnt(5)
	v_mfma_f32_32x32x16_bf16 v[48:63], v[240:243], v[84:87], v[48:63]
	ds_read_b128 v[240:243], v233 offset:44128
	s_waitcnt lgkmcnt(5)
	v_mfma_f32_32x32x16_bf16 v[32:47], v[88:91], v[84:87], v[32:47]
	ds_read_b128 v[88:91], v233 offset:48736
	s_waitcnt lgkmcnt(5)
	v_mfma_f32_32x32x16_bf16 v[16:31], v[92:95], v[84:87], v[16:31]
	s_waitcnt lgkmcnt(4)
	v_mfma_f32_32x32x16_bf16 v[0:15], v[70:73], v[84:87], v[0:15]
	s_waitcnt lgkmcnt(3)
	v_mfma_f32_32x32x16_bf16 v[48:63], v[244:247], v[66:69], v[48:63]
	s_waitcnt lgkmcnt(2)
	v_mfma_f32_32x32x16_bf16 v[32:47], v[236:239], v[66:69], v[32:47]
	s_waitcnt lgkmcnt(1)
	v_mfma_f32_32x32x16_bf16 v[16:31], v[240:243], v[66:69], v[16:31]
	s_waitcnt lgkmcnt(0)
	v_mfma_f32_32x32x16_bf16 v[0:15], v[88:91], v[66:69], v[0:15]
	s_setprio 0
	s_and_b64 s[10:11], s[72:73], s[10:11]
	s_andn2_b64 vcc, exec, s[10:11]
	s_cbranch_vccnz .LBB0_1043
	s_bitcmp1_b32 s12, 0
	s_cselect_b32 s10, 0x11800, 0
	s_add_i32 s10, s10, 0
	v_add3_u32 v66, s10, v201, v162
	s_waitcnt vmcnt(7)
	ds_write_b128 v66, v[128:131]
	v_add3_u32 v66, s10, v203, v182
	s_waitcnt vmcnt(5)
	ds_write_b128 v66, v[132:135] offset:34816
	v_add3_u32 v66, s10, v205, v162
	s_waitcnt vmcnt(3)
	ds_write_b128 v66, v[136:139]
	v_add3_u32 v66, s10, v207, v182
	s_waitcnt vmcnt(1)
	ds_write_b128 v66, v[140:143] offset:34816
	v_add3_u32 v66, s10, v211, v162
	ds_write_b128 v66, v[144:147]
	v_add3_u32 v66, s10, v213, v182
	ds_write_b128 v66, v[148:151] offset:34816
	v_add3_u32 v66, s10, v215, v162
	ds_write_b128 v66, v[152:155]
	v_add3_u32 v66, s10, v217, v182
	s_add_i32 s10, s67, 2
	s_cmp_ge_i32 s10, s65
	s_waitcnt vmcnt(0)
	ds_write_b128 v66, v[156:159] offset:34816
	s_cbranch_scc1 .LBB0_1043
	v_add_u32_e32 v66, s78, v169
	v_mad_u64_u32 v[66:67], s[10:11], s86, v66, 0
	v_lshlrev_b64 v[66:67], 1, v[66:67]
	v_lshl_add_u64 v[68:69], v[192:193], 0, v[66:67]
	s_mul_i32 s10, s78, s32
	s_mov_b32 s11, 0
	v_lshl_add_u64 v[66:67], v[196:197], 0, v[66:67]
	global_load_dwordx4 v[128:131], v[68:69], off
	global_load_dwordx4 v[144:147], v[66:67], off
	v_lshl_add_u64 v[68:69], v[184:185], 0, s[10:11]
	v_lshl_add_u64 v[66:67], v[188:189], 0, s[10:11]
	global_load_dwordx4 v[132:135], v[68:69], off
	global_load_dwordx4 v[148:151], v[66:67], off
	v_add_u32_e32 v68, s78, v173
	v_add_u32_e32 v66, s78, v200
	v_mad_u64_u32 v[68:69], s[14:15], s86, v68, 0
	v_mad_u64_u32 v[66:67], s[14:15], s86, v66, 0
	v_lshl_add_u64 v[68:69], v[68:69], 1, v[194:195]
	v_lshl_add_u64 v[66:67], v[66:67], 1, v[198:199]
	global_load_dwordx4 v[136:139], v[68:69], off
	global_load_dwordx4 v[152:155], v[66:67], off
	v_lshl_add_u64 v[68:69], v[186:187], 0, s[10:11]
	v_lshl_add_u64 v[66:67], v[190:191], 0, s[10:11]
	global_load_dwordx4 v[140:143], v[68:69], off
	global_load_dwordx4 v[156:159], v[66:67], off
